# P5 epilogue: non-temporal hint on the last-use gate_b loads as well
# speedup vs baseline: 1.0048x; 1.0002x over previous
.LBB0_707:
	s_add_i32 s21, s5, s58
	v_or_b32_e32 v156, s21, v160
	v_ashrrev_i32_e32 v157, 31, v156
	v_ashrrev_i32_e32 v155, 31, v154
	v_lshlrev_b64 v[128:129], 12, v[156:157]
	v_lshl_add_u64 v[128:129], s[26:27], 0, v[128:129]
	v_lshlrev_b64 v[154:155], 1, v[154:155]
	v_lshl_add_u64 v[134:135], v[128:129], 0, v[154:155]
	global_load_dwordx4 v[128:131], v[134:135], off offset:2048 nt
	global_load_dwordx4 v[168:171], v[134:135], off offset:2112 nt
	v_or_b32_e32 v132, s21, v163
	v_ashrrev_i32_e32 v133, 31, v132
	v_lshlrev_b64 v[132:133], 11, v[132:133]
	s_ashr_i32 s5, s4, 31
	v_lshl_add_u64 v[132:133], s[94:95], 0, v[132:133]
	v_or_b32_e32 v158, 16, v156
	v_lshl_add_u64 v[132:133], s[4:5], 1, v[132:133]
	v_ashrrev_i32_e32 v159, 31, v158
	v_lshl_add_u64 v[132:133], v[132:133], 0, s[8:9]
	s_movk_i32 s20, 0x4000
	v_lshlrev_b64 v[158:159], 12, v[158:159]
	v_lshl_add_u64 v[132:133], v[132:133], 0, v[144:145]
	v_lshl_add_u64 v[158:159], s[26:27], 0, v[158:159]
	v_lshl_add_u64 v[158:159], v[158:159], 0, v[154:155]
	s_mov_b32 s5, 0x8000
	s_mov_b32 s4, 0xc000
	s_waitcnt vmcnt(0)
	v_lshlrev_b32_e32 v157, 16, v128
	v_and_b32_e32 v128, 0xffff0000, v128
	v_lshlrev_b32_e32 v172, 16, v129
	v_and_b32_e32 v129, 0xffff0000, v129
	v_lshlrev_b32_e32 v173, 16, v130
	v_and_b32_e32 v130, 0xffff0000, v130
	v_lshlrev_b32_e32 v174, 16, v131
	v_and_b32_e32 v131, 0xffff0000, v131
	v_lshlrev_b32_e32 v175, 16, v168
	v_and_b32_e32 v168, 0xffff0000, v168
	v_lshlrev_b32_e32 v176, 16, v169
	v_and_b32_e32 v169, 0xffff0000, v169
	v_lshlrev_b32_e32 v177, 16, v170
	v_and_b32_e32 v170, 0xffff0000, v170
	v_lshlrev_b32_e32 v178, 16, v171
	v_and_b32_e32 v171, 0xffff0000, v171
	v_max_f32_e32 v128, v128, v128
	v_max_f32_e32 v157, v157, v157
	v_max_f32_e32 v179, v129, v129
	v_max_f32_e32 v172, v172, v172
	v_max_f32_e32 v180, v130, v130
	v_max_f32_e32 v173, v173, v173
	v_max_f32_e32 v181, v131, v131
	v_max_f32_e32 v174, v174, v174
	v_max_f32_e32 v182, v168, v168
	v_max_f32_e32 v175, v175, v175
	v_max_f32_e32 v183, v169, v169
	v_max_f32_e32 v176, v176, v176
	v_max_f32_e32 v184, v170, v170
	v_max_f32_e32 v185, v177, v177
	v_max_f32_e32 v186, v171, v171
	v_max_f32_e32 v178, v178, v178
	v_max_f32_e32 v129, 0xda24260, v128
	v_max_f32_e32 v128, 0xda24260, v157
	v_max_f32_e32 v131, 0xda24260, v179
	v_max_f32_e32 v130, 0xda24260, v172
	v_max_f32_e32 v169, 0xda24260, v180
	v_max_f32_e32 v168, 0xda24260, v173
	v_max_f32_e32 v171, 0xda24260, v181
	v_max_f32_e32 v170, 0xda24260, v174
	v_max_f32_e32 v173, 0xda24260, v182
	v_max_f32_e32 v172, 0xda24260, v175
	v_max_f32_e32 v175, 0xda24260, v183
	v_max_f32_e32 v174, 0xda24260, v176
	v_max_f32_e32 v177, 0xda24260, v184
	v_max_f32_e32 v176, 0xda24260, v185
	v_max_f32_e32 v179, 0xda24260, v186
	v_max_f32_e32 v178, 0xda24260, v178
	v_pk_mul_f32 v[126:127], v[126:127], v[130:131]
	v_pk_mul_f32 v[124:125], v[124:125], v[128:129]
	v_pk_mul_f32 v[122:123], v[122:123], v[170:171]
	v_pk_mul_f32 v[120:121], v[120:121], v[168:169]
	v_pk_mul_f32 v[118:119], v[118:119], v[174:175]
	v_pk_mul_f32 v[116:117], v[116:117], v[172:173]
	v_pk_mul_f32 v[128:129], v[114:115], v[178:179]
	v_pk_mul_f32 v[130:131], v[112:113], v[176:177]
	v_cvt_pk_bf16_f32 v112, v124, v125
	v_cvt_pk_bf16_f32 v113, v126, v127
	v_cvt_pk_bf16_f32 v114, v120, v121
	v_cvt_pk_bf16_f32 v115, v122, v123
	v_cvt_pk_bf16_f32 v116, v116, v117
	v_cvt_pk_bf16_f32 v117, v118, v119
	v_cvt_pk_bf16_f32 v118, v130, v131
	v_cvt_pk_bf16_f32 v119, v128, v129
	ds_write_b128 v166, v[112:115]
	ds_write_b128 v166, v[116:119] offset:64
	ds_read_b128 v[112:115], v167
	ds_read_b128 v[116:119], v167 offset:1152
	v_add_co_u32_e32 v120, vcc, s20, v132
	s_nop 1
	v_addc_co_u32_e32 v121, vcc, 0, v133, vcc
	s_waitcnt lgkmcnt(1)
	global_store_dwordx4 v[132:133], v[112:115], off
	s_waitcnt lgkmcnt(0)
	global_store_dwordx4 v[120:121], v[116:119], off
	global_load_dwordx4 v[112:115], v[158:159], off offset:2048 nt
	s_nop 0
	global_load_dwordx4 v[118:121], v[158:159], off offset:2112 nt
	v_or_b32_e32 v116, 32, v156
	v_ashrrev_i32_e32 v117, 31, v116
	v_add_co_u32_e32 v122, vcc, s5, v132
	v_lshlrev_b64 v[116:117], 12, v[116:117]
	s_nop 0
	v_addc_co_u32_e32 v123, vcc, 0, v133, vcc
	v_lshl_add_u64 v[116:117], s[26:27], 0, v[116:117]
	v_lshl_add_u64 v[116:117], v[116:117], 0, v[154:155]
	s_mov_b32 s5, 0x18000
	s_waitcnt vmcnt(1)
	v_lshlrev_b32_e32 v124, 16, v112
	v_and_b32_e32 v112, 0xffff0000, v112
	v_lshlrev_b32_e32 v125, 16, v113
	v_and_b32_e32 v113, 0xffff0000, v113
	v_lshlrev_b32_e32 v126, 16, v114
	v_and_b32_e32 v114, 0xffff0000, v114
	v_lshlrev_b32_e32 v127, 16, v115
	v_and_b32_e32 v115, 0xffff0000, v115
	s_waitcnt vmcnt(0)
	v_lshlrev_b32_e32 v128, 16, v118
	v_and_b32_e32 v118, 0xffff0000, v118
	v_lshlrev_b32_e32 v129, 16, v119
	v_and_b32_e32 v119, 0xffff0000, v119
	v_lshlrev_b32_e32 v130, 16, v120
	v_and_b32_e32 v120, 0xffff0000, v120
	v_lshlrev_b32_e32 v131, 16, v121
	v_and_b32_e32 v121, 0xffff0000, v121
	v_max_f32_e32 v112, v112, v112
	v_max_f32_e32 v124, v124, v124
	v_max_f32_e32 v157, v113, v113
	v_max_f32_e32 v125, v125, v125
	v_max_f32_e32 v158, v114, v114
	v_max_f32_e32 v126, v126, v126
	v_max_f32_e32 v159, v115, v115
	v_max_f32_e32 v127, v127, v127
	v_max_f32_e32 v168, v118, v118
	v_max_f32_e32 v128, v128, v128
	v_max_f32_e32 v169, v119, v119
	v_max_f32_e32 v129, v129, v129
	v_max_f32_e32 v170, v120, v120
	v_max_f32_e32 v130, v130, v130
	v_max_f32_e32 v171, v121, v121
	v_max_f32_e32 v172, v131, v131
	v_max_f32_e32 v113, 0xda24260, v112
	v_max_f32_e32 v112, 0xda24260, v124
	v_max_f32_e32 v115, 0xda24260, v157
	v_max_f32_e32 v114, 0xda24260, v125
	v_max_f32_e32 v119, 0xda24260, v158
	v_max_f32_e32 v118, 0xda24260, v126
	v_max_f32_e32 v121, 0xda24260, v159
	v_max_f32_e32 v120, 0xda24260, v127
	v_max_f32_e32 v125, 0xda24260, v168
	v_max_f32_e32 v124, 0xda24260, v128
	v_max_f32_e32 v127, 0xda24260, v169
	v_max_f32_e32 v126, 0xda24260, v129
	v_max_f32_e32 v129, 0xda24260, v170
	v_max_f32_e32 v128, 0xda24260, v130
	v_max_f32_e32 v131, 0xda24260, v171
	v_max_f32_e32 v130, 0xda24260, v172
	v_pk_mul_f32 v[110:111], v[110:111], v[114:115]
	v_pk_mul_f32 v[108:109], v[108:109], v[112:113]
	v_pk_mul_f32 v[106:107], v[106:107], v[120:121]
	v_pk_mul_f32 v[104:105], v[104:105], v[118:119]
	v_pk_mul_f32 v[102:103], v[102:103], v[126:127]
	v_pk_mul_f32 v[100:101], v[100:101], v[124:125]
	v_pk_mul_f32 v[112:113], v[98:99], v[130:131]
	v_pk_mul_f32 v[114:115], v[96:97], v[128:129]
	v_cvt_pk_bf16_f32 v96, v108, v109
	v_cvt_pk_bf16_f32 v97, v110, v111
	v_cvt_pk_bf16_f32 v98, v104, v105
	v_cvt_pk_bf16_f32 v99, v106, v107
	v_cvt_pk_bf16_f32 v100, v100, v101
	v_cvt_pk_bf16_f32 v101, v102, v103
	v_cvt_pk_bf16_f32 v102, v114, v115
	v_cvt_pk_bf16_f32 v103, v112, v113
	ds_write_b128 v166, v[96:99]
	ds_write_b128 v166, v[100:103] offset:64
	ds_read_b128 v[96:99], v167
	ds_read_b128 v[100:103], v167 offset:1152
	v_add_co_u32_e32 v104, vcc, s4, v132
	s_mov_b32 s4, 0x14000
	s_nop 0
	v_addc_co_u32_e32 v105, vcc, 0, v133, vcc
	s_waitcnt lgkmcnt(1)
	global_store_dwordx4 v[122:123], v[96:99], off
	s_waitcnt lgkmcnt(0)
	global_store_dwordx4 v[104:105], v[100:103], off
	global_load_dwordx4 v[96:99], v[116:117], off offset:2048 nt
	s_nop 0
	global_load_dwordx4 v[102:105], v[116:117], off offset:2112 nt
	v_or_b32_e32 v100, 48, v156
	v_ashrrev_i32_e32 v101, 31, v100
	v_add_co_u32_e32 v106, vcc, s57, v132
	v_lshlrev_b64 v[100:101], 12, v[100:101]
	s_nop 0
	v_addc_co_u32_e32 v107, vcc, 0, v133, vcc
	v_lshl_add_u64 v[100:101], s[26:27], 0, v[100:101]
	v_lshl_add_u64 v[100:101], v[100:101], 0, v[154:155]
	s_waitcnt vmcnt(1)
	v_lshlrev_b32_e32 v108, 16, v96
	v_and_b32_e32 v96, 0xffff0000, v96
	v_lshlrev_b32_e32 v109, 16, v97
	v_and_b32_e32 v97, 0xffff0000, v97
	v_lshlrev_b32_e32 v110, 16, v98
	v_and_b32_e32 v98, 0xffff0000, v98
	v_lshlrev_b32_e32 v111, 16, v99
	v_and_b32_e32 v99, 0xffff0000, v99
	s_waitcnt vmcnt(0)
	v_lshlrev_b32_e32 v112, 16, v102
	v_and_b32_e32 v102, 0xffff0000, v102
	v_lshlrev_b32_e32 v113, 16, v103
	v_and_b32_e32 v103, 0xffff0000, v103
	v_lshlrev_b32_e32 v114, 16, v104
	v_and_b32_e32 v104, 0xffff0000, v104
	v_lshlrev_b32_e32 v115, 16, v105
	v_and_b32_e32 v105, 0xffff0000, v105
	v_max_f32_e32 v96, v96, v96
	v_max_f32_e32 v108, v108, v108
	v_max_f32_e32 v116, v97, v97
	v_max_f32_e32 v109, v109, v109
	v_max_f32_e32 v117, v98, v98
	v_max_f32_e32 v110, v110, v110
	v_max_f32_e32 v118, v99, v99
	v_max_f32_e32 v111, v111, v111
	v_max_f32_e32 v119, v102, v102
	v_max_f32_e32 v112, v112, v112
	v_max_f32_e32 v120, v103, v103
	v_max_f32_e32 v113, v113, v113
	v_max_f32_e32 v121, v104, v104
	v_max_f32_e32 v114, v114, v114
	v_max_f32_e32 v122, v105, v105
	v_max_f32_e32 v123, v115, v115
	v_max_f32_e32 v97, 0xda24260, v96
	v_max_f32_e32 v96, 0xda24260, v108
	v_max_f32_e32 v99, 0xda24260, v116
	v_max_f32_e32 v98, 0xda24260, v109
	v_max_f32_e32 v103, 0xda24260, v117
	v_max_f32_e32 v102, 0xda24260, v110
	v_max_f32_e32 v105, 0xda24260, v118
	v_max_f32_e32 v104, 0xda24260, v111
	v_max_f32_e32 v109, 0xda24260, v119
	v_max_f32_e32 v108, 0xda24260, v112
	v_max_f32_e32 v111, 0xda24260, v120
	v_max_f32_e32 v110, 0xda24260, v113
	v_max_f32_e32 v113, 0xda24260, v121
	v_max_f32_e32 v112, 0xda24260, v114
	v_max_f32_e32 v115, 0xda24260, v122
	v_max_f32_e32 v114, 0xda24260, v123
	v_pk_mul_f32 v[94:95], v[94:95], v[98:99]
	v_pk_mul_f32 v[92:93], v[92:93], v[96:97]
	v_pk_mul_f32 v[90:91], v[90:91], v[104:105]
	v_pk_mul_f32 v[88:89], v[88:89], v[102:103]
	v_pk_mul_f32 v[86:87], v[86:87], v[110:111]
	v_pk_mul_f32 v[84:85], v[84:85], v[108:109]
	v_pk_mul_f32 v[96:97], v[82:83], v[114:115]
	v_pk_mul_f32 v[98:99], v[80:81], v[112:113]
	v_cvt_pk_bf16_f32 v80, v92, v93
	v_cvt_pk_bf16_f32 v81, v94, v95
	v_cvt_pk_bf16_f32 v82, v88, v89
	v_cvt_pk_bf16_f32 v83, v90, v91
	v_cvt_pk_bf16_f32 v84, v84, v85
	v_cvt_pk_bf16_f32 v85, v86, v87
	v_cvt_pk_bf16_f32 v86, v98, v99
	v_cvt_pk_bf16_f32 v87, v96, v97
	ds_write_b128 v166, v[80:83]
	ds_write_b128 v166, v[84:87] offset:64
	ds_read_b128 v[80:83], v167
	ds_read_b128 v[84:87], v167 offset:1152
	v_add_co_u32_e32 v88, vcc, s4, v132
	s_mov_b32 s4, 0x1c000
	s_nop 0
	v_addc_co_u32_e32 v89, vcc, 0, v133, vcc
	s_waitcnt lgkmcnt(1)
	global_store_dwordx4 v[106:107], v[80:83], off
	s_waitcnt lgkmcnt(0)
	global_store_dwordx4 v[88:89], v[84:87], off
	global_load_dwordx4 v[80:83], v[100:101], off offset:2048 nt
	s_nop 0
	global_load_dwordx4 v[86:89], v[100:101], off offset:2112 nt
	v_add_co_u32_e32 v90, vcc, s5, v132
	v_lshl_add_u64 v[84:85], v[134:135], 0, s[28:29]
	s_nop 0
	v_addc_co_u32_e32 v91, vcc, 0, v133, vcc
	s_mov_b32 s5, 0x40000
	s_waitcnt vmcnt(1)
	v_lshlrev_b32_e32 v92, 16, v80
	v_and_b32_e32 v80, 0xffff0000, v80
	v_lshlrev_b32_e32 v93, 16, v81
	v_and_b32_e32 v81, 0xffff0000, v81
	v_lshlrev_b32_e32 v94, 16, v82
	v_and_b32_e32 v82, 0xffff0000, v82
	v_lshlrev_b32_e32 v95, 16, v83
	v_and_b32_e32 v83, 0xffff0000, v83
	s_waitcnt vmcnt(0)
	v_lshlrev_b32_e32 v96, 16, v86
	v_and_b32_e32 v86, 0xffff0000, v86
	v_lshlrev_b32_e32 v97, 16, v87
	v_and_b32_e32 v87, 0xffff0000, v87
	v_lshlrev_b32_e32 v98, 16, v88
	v_and_b32_e32 v88, 0xffff0000, v88
	v_lshlrev_b32_e32 v99, 16, v89
	v_and_b32_e32 v89, 0xffff0000, v89
	v_max_f32_e32 v80, v80, v80
	v_max_f32_e32 v92, v92, v92
	v_max_f32_e32 v100, v81, v81
	v_max_f32_e32 v93, v93, v93
	v_max_f32_e32 v101, v82, v82
	v_max_f32_e32 v94, v94, v94
	v_max_f32_e32 v102, v83, v83
	v_max_f32_e32 v95, v95, v95
	v_max_f32_e32 v103, v86, v86
	v_max_f32_e32 v96, v96, v96
	v_max_f32_e32 v104, v87, v87
	v_max_f32_e32 v97, v97, v97
	v_max_f32_e32 v105, v88, v88
	v_max_f32_e32 v98, v98, v98
	v_max_f32_e32 v106, v89, v89
	v_max_f32_e32 v107, v99, v99
	v_max_f32_e32 v81, 0xda24260, v80
	v_max_f32_e32 v80, 0xda24260, v92
	v_max_f32_e32 v83, 0xda24260, v100
	v_max_f32_e32 v82, 0xda24260, v93
	v_max_f32_e32 v87, 0xda24260, v101
	v_max_f32_e32 v86, 0xda24260, v94
	v_max_f32_e32 v89, 0xda24260, v102
	v_max_f32_e32 v88, 0xda24260, v95
	v_max_f32_e32 v93, 0xda24260, v103
	v_max_f32_e32 v92, 0xda24260, v96
	v_max_f32_e32 v95, 0xda24260, v104
	v_max_f32_e32 v94, 0xda24260, v97
	v_max_f32_e32 v97, 0xda24260, v105
	v_max_f32_e32 v96, 0xda24260, v98
	v_max_f32_e32 v99, 0xda24260, v106
	v_max_f32_e32 v98, 0xda24260, v107
	v_pk_mul_f32 v[78:79], v[78:79], v[82:83]
	v_pk_mul_f32 v[76:77], v[76:77], v[80:81]
	v_pk_mul_f32 v[74:75], v[74:75], v[88:89]
	v_pk_mul_f32 v[72:73], v[72:73], v[86:87]
	v_pk_mul_f32 v[70:71], v[70:71], v[94:95]
	v_pk_mul_f32 v[68:69], v[68:69], v[92:93]
	v_pk_mul_f32 v[80:81], v[66:67], v[98:99]
	v_pk_mul_f32 v[82:83], v[64:65], v[96:97]
	v_cvt_pk_bf16_f32 v64, v76, v77
	v_cvt_pk_bf16_f32 v65, v78, v79
	v_cvt_pk_bf16_f32 v66, v72, v73
	v_cvt_pk_bf16_f32 v67, v74, v75
	v_cvt_pk_bf16_f32 v68, v68, v69
	v_cvt_pk_bf16_f32 v69, v70, v71
	v_cvt_pk_bf16_f32 v70, v82, v83
	v_cvt_pk_bf16_f32 v71, v80, v81
	ds_write_b128 v166, v[64:67]
	ds_write_b128 v166, v[68:71] offset:64
	ds_read_b128 v[64:67], v167
	ds_read_b128 v[68:71], v167 offset:1152
	v_add_co_u32_e32 v72, vcc, s4, v132
	s_mov_b32 s4, 0x44000
	s_nop 0
	v_addc_co_u32_e32 v73, vcc, 0, v133, vcc
	s_waitcnt lgkmcnt(1)
	global_store_dwordx4 v[90:91], v[64:67], off
	s_waitcnt lgkmcnt(0)
	global_store_dwordx4 v[72:73], v[68:71], off
	global_load_dwordx4 v[64:67], v[84:85], off offset:2048 nt
	s_nop 0
	global_load_dwordx4 v[70:73], v[84:85], off offset:2112 nt
	v_add_co_u32_e32 v74, vcc, s5, v132
	v_lshl_add_u64 v[68:69], v[134:135], 0, s[30:31]
	s_nop 0
	v_addc_co_u32_e32 v75, vcc, 0, v133, vcc
	s_waitcnt vmcnt(1)
	v_lshlrev_b32_e32 v76, 16, v64
	v_and_b32_e32 v64, 0xffff0000, v64
	v_lshlrev_b32_e32 v77, 16, v65
	v_and_b32_e32 v65, 0xffff0000, v65
	v_lshlrev_b32_e32 v78, 16, v66
	v_and_b32_e32 v66, 0xffff0000, v66
	v_lshlrev_b32_e32 v79, 16, v67
	v_and_b32_e32 v67, 0xffff0000, v67
	s_waitcnt vmcnt(0)
	v_lshlrev_b32_e32 v80, 16, v70
	v_and_b32_e32 v70, 0xffff0000, v70
	v_lshlrev_b32_e32 v81, 16, v71
	v_and_b32_e32 v71, 0xffff0000, v71
	v_lshlrev_b32_e32 v82, 16, v72
	v_and_b32_e32 v72, 0xffff0000, v72
	v_lshlrev_b32_e32 v83, 16, v73
	v_and_b32_e32 v73, 0xffff0000, v73
	v_max_f32_e32 v64, v64, v64
	v_max_f32_e32 v76, v76, v76
	v_max_f32_e32 v84, v65, v65
	v_max_f32_e32 v77, v77, v77
	v_max_f32_e32 v85, v66, v66
	v_max_f32_e32 v78, v78, v78
	v_max_f32_e32 v86, v67, v67
	v_max_f32_e32 v79, v79, v79
	v_max_f32_e32 v87, v70, v70
	v_max_f32_e32 v80, v80, v80
	v_max_f32_e32 v88, v71, v71
	v_max_f32_e32 v81, v81, v81
	v_max_f32_e32 v89, v72, v72
	v_max_f32_e32 v82, v82, v82
	v_max_f32_e32 v90, v73, v73
	v_max_f32_e32 v91, v83, v83
	v_max_f32_e32 v65, 0xda24260, v64
	v_max_f32_e32 v64, 0xda24260, v76
	v_max_f32_e32 v67, 0xda24260, v84
	v_max_f32_e32 v66, 0xda24260, v77
	v_max_f32_e32 v71, 0xda24260, v85
	v_max_f32_e32 v70, 0xda24260, v78
	v_max_f32_e32 v73, 0xda24260, v86
	v_max_f32_e32 v72, 0xda24260, v79
	v_max_f32_e32 v77, 0xda24260, v87
	v_max_f32_e32 v76, 0xda24260, v80
	v_max_f32_e32 v79, 0xda24260, v88
	v_max_f32_e32 v78, 0xda24260, v81
	v_max_f32_e32 v81, 0xda24260, v89
	v_max_f32_e32 v80, 0xda24260, v82
	v_max_f32_e32 v83, 0xda24260, v90
	v_max_f32_e32 v82, 0xda24260, v91
	v_pk_mul_f32 v[62:63], v[62:63], v[66:67]
	v_pk_mul_f32 v[60:61], v[60:61], v[64:65]
	v_pk_mul_f32 v[58:59], v[58:59], v[72:73]
	v_pk_mul_f32 v[56:57], v[56:57], v[70:71]
	v_pk_mul_f32 v[54:55], v[54:55], v[78:79]
	v_pk_mul_f32 v[52:53], v[52:53], v[76:77]
	v_pk_mul_f32 v[64:65], v[50:51], v[82:83]
	v_pk_mul_f32 v[66:67], v[48:49], v[80:81]
	v_cvt_pk_bf16_f32 v48, v60, v61
	v_cvt_pk_bf16_f32 v49, v62, v63
	v_cvt_pk_bf16_f32 v50, v56, v57
	v_cvt_pk_bf16_f32 v51, v58, v59
	v_cvt_pk_bf16_f32 v52, v52, v53
	v_cvt_pk_bf16_f32 v53, v54, v55
	v_cvt_pk_bf16_f32 v54, v66, v67
	v_cvt_pk_bf16_f32 v55, v64, v65
	ds_write_b128 v166, v[48:51]
	ds_write_b128 v166, v[52:55] offset:64
	ds_read_b128 v[48:51], v167
	ds_read_b128 v[52:55], v167 offset:1152
	v_add_co_u32_e32 v56, vcc, s4, v132
	s_mov_b32 s4, 0x48000
	s_nop 0
	v_addc_co_u32_e32 v57, vcc, 0, v133, vcc
	s_waitcnt lgkmcnt(1)
	global_store_dwordx4 v[74:75], v[48:51], off
	s_waitcnt lgkmcnt(0)
	global_store_dwordx4 v[56:57], v[52:55], off
	global_load_dwordx4 v[48:51], v[68:69], off offset:2048 nt
	s_nop 0
	global_load_dwordx4 v[54:57], v[68:69], off offset:2112 nt
	v_add_co_u32_e32 v58, vcc, s4, v132
	v_lshl_add_u64 v[52:53], v[134:135], 0, s[36:37]
	s_nop 0
	v_addc_co_u32_e32 v59, vcc, 0, v133, vcc
	s_waitcnt vmcnt(1)
	v_lshlrev_b32_e32 v60, 16, v48
	v_and_b32_e32 v48, 0xffff0000, v48
	v_lshlrev_b32_e32 v61, 16, v49
	v_and_b32_e32 v49, 0xffff0000, v49
	v_lshlrev_b32_e32 v62, 16, v50
	v_and_b32_e32 v50, 0xffff0000, v50
	v_lshlrev_b32_e32 v63, 16, v51
	v_and_b32_e32 v51, 0xffff0000, v51
	s_waitcnt vmcnt(0)
	v_lshlrev_b32_e32 v64, 16, v54
	v_and_b32_e32 v54, 0xffff0000, v54
	v_lshlrev_b32_e32 v65, 16, v55
	v_and_b32_e32 v55, 0xffff0000, v55
	v_lshlrev_b32_e32 v66, 16, v56
	v_and_b32_e32 v56, 0xffff0000, v56
	v_lshlrev_b32_e32 v67, 16, v57
	v_and_b32_e32 v57, 0xffff0000, v57
	v_max_f32_e32 v48, v48, v48
	v_max_f32_e32 v60, v60, v60
	v_max_f32_e32 v68, v49, v49
	v_max_f32_e32 v61, v61, v61
	v_max_f32_e32 v69, v50, v50
	v_max_f32_e32 v62, v62, v62
	v_max_f32_e32 v70, v51, v51
	v_max_f32_e32 v63, v63, v63
	v_max_f32_e32 v71, v54, v54
	v_max_f32_e32 v64, v64, v64
	v_max_f32_e32 v72, v55, v55
	v_max_f32_e32 v65, v65, v65
	v_max_f32_e32 v73, v56, v56
	v_max_f32_e32 v66, v66, v66
	v_max_f32_e32 v74, v57, v57
	v_max_f32_e32 v75, v67, v67
	v_max_f32_e32 v49, 0xda24260, v48
	v_max_f32_e32 v48, 0xda24260, v60
	v_max_f32_e32 v51, 0xda24260, v68
	v_max_f32_e32 v50, 0xda24260, v61
	v_max_f32_e32 v55, 0xda24260, v69
	v_max_f32_e32 v54, 0xda24260, v62
	v_max_f32_e32 v57, 0xda24260, v70
	v_max_f32_e32 v56, 0xda24260, v63
	v_max_f32_e32 v61, 0xda24260, v71
	v_max_f32_e32 v60, 0xda24260, v64
	v_max_f32_e32 v63, 0xda24260, v72
	v_max_f32_e32 v62, 0xda24260, v65
	v_max_f32_e32 v65, 0xda24260, v73
	v_max_f32_e32 v64, 0xda24260, v66
	v_max_f32_e32 v67, 0xda24260, v74
	v_max_f32_e32 v66, 0xda24260, v75
	v_pk_mul_f32 v[46:47], v[46:47], v[50:51]
	v_pk_mul_f32 v[44:45], v[44:45], v[48:49]
	v_pk_mul_f32 v[42:43], v[42:43], v[56:57]
	v_pk_mul_f32 v[40:41], v[40:41], v[54:55]
	v_pk_mul_f32 v[38:39], v[38:39], v[62:63]
	v_pk_mul_f32 v[36:37], v[36:37], v[60:61]
	v_pk_mul_f32 v[48:49], v[34:35], v[66:67]
	v_pk_mul_f32 v[50:51], v[32:33], v[64:65]
	v_cvt_pk_bf16_f32 v32, v44, v45
	v_cvt_pk_bf16_f32 v33, v46, v47
	v_cvt_pk_bf16_f32 v34, v40, v41
	v_cvt_pk_bf16_f32 v35, v42, v43
	v_cvt_pk_bf16_f32 v36, v36, v37
	v_cvt_pk_bf16_f32 v37, v38, v39
	v_cvt_pk_bf16_f32 v38, v50, v51
	v_cvt_pk_bf16_f32 v39, v48, v49
	ds_write_b128 v166, v[32:35]
	ds_write_b128 v166, v[36:39] offset:64
	ds_read_b128 v[32:35], v167
	ds_read_b128 v[36:39], v167 offset:1152
	v_add_co_u32_e32 v40, vcc, s63, v132
	s_nop 1
	v_addc_co_u32_e32 v41, vcc, 0, v133, vcc
	s_waitcnt lgkmcnt(1)
	global_store_dwordx4 v[58:59], v[32:35], off
	s_waitcnt lgkmcnt(0)
	global_store_dwordx4 v[40:41], v[36:39], off
	global_load_dwordx4 v[32:35], v[52:53], off offset:2048 nt
	s_nop 0
	global_load_dwordx4 v[38:41], v[52:53], off offset:2112 nt
	v_add_co_u32_e32 v42, vcc, s64, v132
	v_lshl_add_u64 v[36:37], v[134:135], 0, s[38:39]
	s_nop 0
	v_addc_co_u32_e32 v43, vcc, 0, v133, vcc
	s_waitcnt vmcnt(1)
	v_lshlrev_b32_e32 v44, 16, v32
	v_and_b32_e32 v32, 0xffff0000, v32
	v_lshlrev_b32_e32 v45, 16, v33
	v_and_b32_e32 v33, 0xffff0000, v33
	v_lshlrev_b32_e32 v46, 16, v34
	v_and_b32_e32 v34, 0xffff0000, v34
	v_lshlrev_b32_e32 v47, 16, v35
	v_and_b32_e32 v35, 0xffff0000, v35
	s_waitcnt vmcnt(0)
	v_lshlrev_b32_e32 v48, 16, v38
	v_and_b32_e32 v38, 0xffff0000, v38
	v_lshlrev_b32_e32 v49, 16, v39
	v_and_b32_e32 v39, 0xffff0000, v39
	v_lshlrev_b32_e32 v50, 16, v40
	v_and_b32_e32 v40, 0xffff0000, v40
	v_lshlrev_b32_e32 v51, 16, v41
	v_and_b32_e32 v41, 0xffff0000, v41
	v_max_f32_e32 v32, v32, v32
	v_max_f32_e32 v44, v44, v44
	v_max_f32_e32 v52, v33, v33
	v_max_f32_e32 v45, v45, v45
	v_max_f32_e32 v53, v34, v34
	v_max_f32_e32 v46, v46, v46
	v_max_f32_e32 v54, v35, v35
	v_max_f32_e32 v47, v47, v47
	v_max_f32_e32 v55, v38, v38
	v_max_f32_e32 v48, v48, v48
	v_max_f32_e32 v56, v39, v39
	v_max_f32_e32 v49, v49, v49
	v_max_f32_e32 v57, v40, v40
	v_max_f32_e32 v50, v50, v50
	v_max_f32_e32 v58, v41, v41
	v_max_f32_e32 v59, v51, v51
	v_max_f32_e32 v33, 0xda24260, v32
	v_max_f32_e32 v32, 0xda24260, v44
	v_max_f32_e32 v35, 0xda24260, v52
	v_max_f32_e32 v34, 0xda24260, v45
	v_max_f32_e32 v39, 0xda24260, v53
	v_max_f32_e32 v38, 0xda24260, v46
	v_max_f32_e32 v41, 0xda24260, v54
	v_max_f32_e32 v40, 0xda24260, v47
	v_max_f32_e32 v45, 0xda24260, v55
	v_max_f32_e32 v44, 0xda24260, v48
	v_max_f32_e32 v47, 0xda24260, v56
	v_max_f32_e32 v46, 0xda24260, v49
	v_max_f32_e32 v49, 0xda24260, v57
	v_max_f32_e32 v48, 0xda24260, v50
	v_max_f32_e32 v51, 0xda24260, v58
	v_max_f32_e32 v50, 0xda24260, v59
	v_pk_mul_f32 v[30:31], v[30:31], v[34:35]
	v_pk_mul_f32 v[28:29], v[28:29], v[32:33]
	v_pk_mul_f32 v[26:27], v[26:27], v[40:41]
	v_pk_mul_f32 v[24:25], v[24:25], v[38:39]
	v_pk_mul_f32 v[22:23], v[22:23], v[46:47]
	v_pk_mul_f32 v[20:21], v[20:21], v[44:45]
	v_pk_mul_f32 v[32:33], v[18:19], v[50:51]
	v_pk_mul_f32 v[34:35], v[16:17], v[48:49]
	v_cvt_pk_bf16_f32 v16, v28, v29
	v_cvt_pk_bf16_f32 v17, v30, v31
	v_cvt_pk_bf16_f32 v18, v24, v25
	v_cvt_pk_bf16_f32 v19, v26, v27
	v_cvt_pk_bf16_f32 v20, v20, v21
	v_cvt_pk_bf16_f32 v21, v22, v23
	v_cvt_pk_bf16_f32 v22, v34, v35
	v_cvt_pk_bf16_f32 v23, v32, v33
	ds_write_b128 v166, v[16:19]
	ds_write_b128 v166, v[20:23] offset:64
	ds_read_b128 v[16:19], v167
	ds_read_b128 v[20:23], v167 offset:1152
	v_add_co_u32_e32 v24, vcc, s65, v132
	s_nop 1
	v_addc_co_u32_e32 v25, vcc, 0, v133, vcc
	s_waitcnt lgkmcnt(1)
	global_store_dwordx4 v[42:43], v[16:19], off
	s_waitcnt lgkmcnt(0)
	global_store_dwordx4 v[24:25], v[20:23], off
	global_load_dwordx4 v[16:19], v[36:37], off offset:2048 nt
	s_nop 0
	global_load_dwordx4 v[24:27], v[36:37], off offset:2112 nt
	v_add_co_u32_e32 v20, vcc, 0x58000, v132
	s_waitcnt vmcnt(1)
	v_lshlrev_b32_e32 v23, 16, v16
	v_and_b32_e32 v16, 0xffff0000, v16
	v_lshlrev_b32_e32 v28, 16, v17
	v_and_b32_e32 v17, 0xffff0000, v17
	v_lshlrev_b32_e32 v29, 16, v18
	v_and_b32_e32 v18, 0xffff0000, v18
	v_lshlrev_b32_e32 v30, 16, v19
	v_and_b32_e32 v19, 0xffff0000, v19
	s_waitcnt vmcnt(0)
	v_lshlrev_b32_e32 v31, 16, v24
	v_and_b32_e32 v24, 0xffff0000, v24
	v_lshlrev_b32_e32 v32, 16, v25
	v_and_b32_e32 v25, 0xffff0000, v25
	v_lshlrev_b32_e32 v33, 16, v26
	v_and_b32_e32 v26, 0xffff0000, v26
	v_lshlrev_b32_e32 v34, 16, v27
	v_and_b32_e32 v27, 0xffff0000, v27
	v_max_f32_e32 v16, v16, v16
	v_max_f32_e32 v23, v23, v23
	v_max_f32_e32 v35, v17, v17
	v_max_f32_e32 v28, v28, v28
	v_max_f32_e32 v36, v18, v18
	v_max_f32_e32 v29, v29, v29
	v_max_f32_e32 v37, v19, v19
	v_max_f32_e32 v30, v30, v30
	v_max_f32_e32 v38, v24, v24
	v_max_f32_e32 v31, v31, v31
	v_max_f32_e32 v39, v25, v25
	v_max_f32_e32 v32, v32, v32
	v_max_f32_e32 v40, v26, v26
	v_max_f32_e32 v41, v33, v33
	v_max_f32_e32 v42, v27, v27
	v_max_f32_e32 v34, v34, v34
	v_max_f32_e32 v17, 0xda24260, v16
	v_max_f32_e32 v16, 0xda24260, v23
	v_max_f32_e32 v19, 0xda24260, v35
	v_max_f32_e32 v18, 0xda24260, v28
	v_max_f32_e32 v25, 0xda24260, v36
	v_max_f32_e32 v24, 0xda24260, v29
	v_max_f32_e32 v27, 0xda24260, v37
	v_max_f32_e32 v26, 0xda24260, v30
	v_max_f32_e32 v29, 0xda24260, v38
	v_max_f32_e32 v28, 0xda24260, v31
	v_max_f32_e32 v31, 0xda24260, v39
	v_max_f32_e32 v30, 0xda24260, v32
	v_max_f32_e32 v33, 0xda24260, v40
	v_max_f32_e32 v32, 0xda24260, v41
	v_max_f32_e32 v35, 0xda24260, v42
	v_max_f32_e32 v34, 0xda24260, v34
	v_pk_mul_f32 v[14:15], v[14:15], v[18:19]
	v_pk_mul_f32 v[12:13], v[12:13], v[16:17]
	v_pk_mul_f32 v[10:11], v[10:11], v[26:27]
	v_pk_mul_f32 v[8:9], v[8:9], v[24:25]
	v_pk_mul_f32 v[6:7], v[6:7], v[30:31]
	v_pk_mul_f32 v[4:5], v[4:5], v[28:29]
	v_pk_mul_f32 v[16:17], v[2:3], v[34:35]
	v_pk_mul_f32 v[18:19], v[0:1], v[32:33]
	v_cvt_pk_bf16_f32 v0, v12, v13
	v_cvt_pk_bf16_f32 v1, v14, v15
	v_cvt_pk_bf16_f32 v2, v8, v9
	v_cvt_pk_bf16_f32 v3, v10, v11
	v_cvt_pk_bf16_f32 v4, v4, v5
	v_cvt_pk_bf16_f32 v5, v6, v7
	v_cvt_pk_bf16_f32 v6, v18, v19
	v_cvt_pk_bf16_f32 v7, v16, v17
	ds_write_b128 v166, v[0:3]
	ds_write_b128 v166, v[4:7] offset:64
	ds_read_b128 v[0:3], v167
	ds_read_b128 v[4:7], v167 offset:1152
	v_addc_co_u32_e32 v21, vcc, 0, v133, vcc
	v_add_co_u32_e32 v22, vcc, 0x5c000, v132
	s_nop 1
	v_addc_co_u32_e32 v23, vcc, 0, v133, vcc
	s_and_b64 vcc, exec, s[0:1]
	s_mov_b64 s[0:1], -1
	s_waitcnt lgkmcnt(1)
	global_store_dwordx4 v[20:21], v[0:3], off
	s_waitcnt lgkmcnt(0)
	global_store_dwordx4 v[22:23], v[4:7], off
	s_cbranch_vccnz .LBB0_696
	s_andn2_b64 vcc, exec, s[10:11]
	s_cbranch_vccnz .LBB0_695
	s_barrier
	s_branch .LBB0_695
